# NSA steps: second s_barrier per step (before exp/PV half) plus a one-barrier skew between the two virtual blocks so their S/softmax and exp/PV halves overlap
# speedup vs baseline: 1.0845x; 1.0020x over previous
; DEVI void nsa_item(const Params& p, int l, int item, char* lds_raw, volatile int* nsa_cnt) {
;     ...
;     for (; j <= qt; ++j) {
;       KV_STORE(kvo);
;       __syncthreads();
;       if (j < qt) {
;         int jn = j + 1;
;         KV_LOAD(kbase, vbase, jn);
;       }
;       attn_step(st, qf, Kb + kvo, Vb + kvo, (j == qt) ? tokl : 63, (j == qt - 8) ? tokl : -1, fr, fq);
;       kvo ^= 64 * LS;
;     }
; #pragma unroll
;     for (int g = 0; g < 2; ++g) {
;       const float lsum = attn_rowsum(st, g);
;       float sc = (lsum > 0.f ? 1.f / lsum : 0.f) * gate[g][2];
; #pragma unroll
;       for (int d = 0; d < 4; ++d) fin[g][d] += st.o[g][d] * sc;
;     }
.LBB0_479:
	v_readfirstlane_b32 s0, v220
	s_lshr_b32 s0, s0, 8
	s_cmp_lg_u32 s0, 0
	s_cbranch_scc1 .Lwin_skew_out
	s_barrier

; DEVI int vhalf() { int t = threadIdx.x >> 8; t = __builtin_amdgcn_readfirstlane(t); return t; }
; DEVI void nsa_item(const Params& p, int l, int item, char* lds_raw, volatile int* nsa_cnt) {
;     ...
;   int kvo = 0;
;   {
;     AttnState st;
;     attn_init(st);
;     const bfu* kbase = proj + tokbase * LDP + C_KS + h * 64;
;     const bfu* vbase = (const bfu*)(p.ws + OFF_VST) + ((long)b * 128 + h * 64) * SEQ;
;     unsigned rem = ormask & ((2u << qt) - 1u);
;     if (tid == 0) nsa_cnt[vhalf()] = __popc(rem);
;     __syncthreads();
;     const int niter = max(nsa_cnt[0], nsa_cnt[1]);
;     int j = __ffs(rem) - 1;
;     KV_LOAD(kbase, vbase, j);
.LBB0_500:
	s_or_b64 exec, exec, s[0:1]
	s_mov_b64 s[0:1], src_shared_base
	v_mov_b32_e32 v179, s1
	v_mov_b32_e32 v181, s1
	s_waitcnt lgkmcnt(0)
	s_barrier
	flat_load_dword v82, v[178:179] sc0 sc1
	s_waitcnt vmcnt(0)
	flat_load_dword v84, v[180:181] sc0 sc1
	s_waitcnt vmcnt(0)
	s_mul_i32 s0, s20, 0xc00000
	v_ashrrev_i32_e32 v186, 3, v83
	s_add_u32 s0, s6, s0
	v_add_u32_e32 v142, 32, v186
	s_addc_u32 s1, s7, 0
	v_mov_b32_e32 v66, v1
	v_mov_b32_e32 v67, v1
	v_mov_b32_e32 v68, v1
	v_mov_b32_e32 v69, v1
	v_ashrrev_i32_e32 v143, 31, v142
	s_add_u32 s36, s0, s11
	v_ashrrev_i32_e32 v187, 31, v186
	v_mov_b64_e32 v[62:63], v[66:67]
	v_mov_b64_e32 v[58:59], v[66:67]
	v_mov_b64_e32 v[50:51], v[66:67]
	v_mov_b64_e32 v[80:81], v[68:69]
	v_mov_b64_e32 v[76:77], v[68:69]
	v_mov_b64_e32 v[72:73], v[68:69]
	v_mov_b64_e32 v[54:55], v[66:67]
	v_mov_b64_e32 v[104:105], v[68:69]
	v_lshlrev_b64 v[146:147], 11, v[142:143]
	s_addc_u32 s37, s1, 0
	s_lshl_b32 s0, s20, 18
	s_lshl_b32 s1, s23, 17
	v_mov_b64_e32 v[108:109], v[68:69]
	v_mov_b32_e32 v179, 0
	v_mov_b64_e32 v[64:65], v[68:69]
	v_mov_b64_e32 v[60:61], v[68:69]
	v_mov_b64_e32 v[52:53], v[68:69]
	v_mov_b64_e32 v[78:79], v[66:67]
	v_mov_b64_e32 v[74:75], v[66:67]
	v_mov_b64_e32 v[70:71], v[66:67]
	v_mov_b64_e32 v[56:57], v[68:69]
	v_mov_b64_e32 v[102:103], v[66:67]
	v_lshlrev_b64 v[144:145], 11, v[186:187]
	s_or_b32 s20, s0, s1
	v_lshl_add_u64 v[188:189], s[36:37], 0, v[0:1]
	v_mov_b64_e32 v[106:107], v[66:67]
	s_waitcnt lgkmcnt(0)
	v_max_i32_e32 v143, v82, v84
	v_cmp_lt_i32_e32 vcc, 0, v143
	s_and_saveexec_b64 s[64:65], vcc
	s_cbranch_execz .LBB0_517
	s_lshl_b32 s0, s20, 1
	v_readlane_b32 s1, v243, 18
	s_add_u32 s0, s1, s0
	v_readlane_b32 s1, v243, 19
	s_addc_u32 s1, s1, 0
	v_cmp_eq_u32_e32 vcc, 0, v153
	v_lshl_add_u64 v[50:51], v[144:145], 1, s[0:1]
	v_lshl_add_u64 v[52:53], v[146:147], 1, s[0:1]
	s_ff1_i32_b32 s0, s4
	s_lshl_b32 s0, s0, 6
	s_cmp_lg_u32 s4, 0
	s_cselect_b32 s0, s0, 0xffffffc0
	s_ashr_i32 s1, s0, 31
	s_lshl_b64 s[38:39], s[0:1], 1
	v_lshl_add_u64 v[54:55], v[52:53], 0, s[38:39]
	v_lshl_add_u64 v[56:57], v[50:51], 0, s[38:39]
	v_lshl_add_u64 v[54:55], v[54:55], 0, v[0:1]
	v_lshl_add_u64 v[56:57], v[56:57], 0, v[0:1]
	global_load_dwordx4 v[86:89], v[54:55], off
	global_load_dwordx4 v[90:93], v[56:57], off
	v_add_u32_e32 v56, s0, v142
	v_mov_b64_e32 v[54:55], s[36:37]
	v_mad_i64_i32 v[56:57], s[38:39], v56, s72, v[54:55]
	v_add_u32_e32 v58, s0, v186
	v_lshl_add_u64 v[56:57], v[56:57], 0, v[0:1]
	v_mad_i64_i32 v[54:55], s[0:1], v58, s72, v[54:55]
	v_lshl_add_u64 v[54:55], v[54:55], 0, v[0:1]
	global_load_dwordx4 v[94:97], v[56:57], off offset:2048
	global_load_dwordx4 v[98:101], v[54:55], off offset:2048
	v_lshl_add_u64 v[148:149], v[50:51], 0, v[0:1]
	v_cndmask_b32_e32 v50, 0, v228, vcc
	s_movk_i32 s0, 0x90
	v_perm_b32 v82, v50, v50, s16
	v_mul_lo_u32 v50, v186, s0
	v_mov_b32_e32 v106, v1
	v_mov_b32_e32 v107, v1
	v_lshl_add_u64 v[150:151], v[52:53], 0, v[0:1]
	v_add_u32_e32 v158, s26, v50
	v_mov_b32_e32 v108, v1
	v_mov_b32_e32 v109, v1
	v_mov_b64_e32 v[102:103], v[106:107]
	v_mov_b64_e32 v[54:55], v[106:107]
	v_mov_b64_e32 v[70:71], v[106:107]
	v_mov_b64_e32 v[74:75], v[106:107]
	v_mov_b64_e32 v[78:79], v[106:107]
	v_mov_b64_e32 v[50:51], v[106:107]
	v_mov_b64_e32 v[58:59], v[106:107]
	v_mov_b64_e32 v[62:63], v[106:107]
	v_mov_b64_e32 v[66:67], v[106:107]
	s_mov_b32 s23, 0
	v_mov_b32_e32 v83, v82
	v_mov_b32_e32 v84, v82
	v_mov_b32_e32 v85, v82
	v_mov_b32_e32 v152, 0xf149f2ca
	s_mov_b64 s[66:67], 0
	v_mov_b64_e32 v[104:105], v[108:109]
	v_mov_b64_e32 v[56:57], v[108:109]
	v_mov_b64_e32 v[72:73], v[108:109]
	v_mov_b64_e32 v[76:77], v[108:109]
	v_mov_b64_e32 v[80:81], v[108:109]
	v_mov_b64_e32 v[52:53], v[108:109]
	v_mov_b64_e32 v[60:61], v[108:109]
	v_mov_b64_e32 v[64:65], v[108:109]
	v_mov_b64_e32 v[68:69], v[108:109]
	v_mov_b32_e32 v154, 0xf149f2ca
	v_readfirstlane_b32 s30, v220
	s_lshr_b32 s30, s30, 8
	s_cmp_lg_u32 s30, 1
	s_cbranch_scc1 .Lsel_skew_in
	s_barrier

; DEVI void nsa_item(const Params& p, int l, int item, char* lds_raw, volatile int* nsa_cnt) {
;     ...
;     for (int itx = 0; itx < niter; ++itx) {
;       const bool active = (rem != 0u);
;       if (active) { j = __ffs(rem) - 1; rem &= rem - 1; }
;       if (active) KV_STORE(kvo);
;       __syncthreads();
;       if (active) {
;         if (rem) {
;           int jn = __ffs(rem) - 1;
;           KV_LOAD(kbase, vbase, jn);
;         }
;         const bool insel = (mysel >> j) & 1u;
;         const int hi = insel ? ((j == qt) ? tokl : 63) : -1;
;         if (__builtin_amdgcn_ballot_w64(insel) != 0ull) attn_step(st, qf, Kb + kvo, Vb + kvo, hi, -1, fr, fq);
.LBB0_502:
	s_barrier
	v_mov_b32_e32 v159, v152
	v_mov_b32_e32 v160, v154

; template <bool WITH_L>
; DEVI void pv_accum_t(f32x4 (&o)[2][4], f32x4 (&ol)[2], const f32x4 (&pr)[2][4], const bfu* Vt, int fr, int fq) {
; #pragma unroll
;   for (int kp = 0; kp < 2; ++kp) {
;     bf16x8 pf[2];
; #pragma unroll
;     for (int g = 0; g < 2; ++g) {
;       uint4 u;
;       u.x = pack2(pr[g][2 * kp][0], pr[g][2 * kp][1]);
;       u.y = pack2(pr[g][2 * kp][2], pr[g][2 * kp][3]);
;       u.z = pack2(pr[g][2 * kp + 1][0], pr[g][2 * kp + 1][1]);
;       u.w = pack2(pr[g][2 * kp + 1][2], pr[g][2 * kp + 1][3]);
;       pf[g] = *(bf16x8*)&u;
;     }
;     if constexpr (WITH_L) {
;       const short one = (fr == 0) ? (short)0x3F80 : (short)0;
;       const bf16x8 vones = {one, one, one, one, one, one, one, one};
; #pragma unroll
;       for (int g = 0; g < 2; ++g) ol[g] = __builtin_amdgcn_mfma_f32_16x16x32_bf16(vones, pf[g], ol[g], 0, 0, 0);
;     }
; #pragma unroll
;     for (int dsub = 0; dsub < 4; ++dsub) {
;       uint2 lo = *(const uint2*)(Vt + (dsub * 16 + fr) * LS + (2 * kp) * 16 + fq * 4);
;       uint2 hi = *(const uint2*)(Vt + (dsub * 16 + fr) * LS + (2 * kp + 1) * 16 + fq * 4);
;       uint4 u; u.x = lo.x; u.y = lo.y; u.z = hi.x; u.w = hi.y;
;       bf16x8 vf = *(bf16x8*)&u;
; #pragma unroll
;       for (int g = 0; g < 2; ++g) o[g][dsub] = __builtin_amdgcn_mfma_f32_16x16x32_bf16(vf, pf[g], o[g][dsub], 0, 0, 0);
;     }
;   }
; DEVI void attn_step(AttnState& st, const bf16x8 (&qf)[2][2], const bfu* Ks, const bfu* Vt, int hi, int lo, int fr, int fq) {
;     ...
;     float mn = fmaxf(st.m[g], mx);
;     float sc = __builtin_amdgcn_exp2f(st.m[g] - mn);
; #pragma unroll
;     for (int ksub = 0; ksub < 4; ++ksub)
; #pragma unroll
;       for (int j = 0; j < 4; ++j) s[g][ksub][j] = __builtin_amdgcn_exp2f(s[g][ksub][j] - mn);
;     st.m[g] = mn;
;     scs[g] = sc;
;   }
;   if (__builtin_amdgcn_ballot_w64((scs[0] != 1.f) || (scs[1] != 1.f)) != 0ull) {
; #pragma unroll
;     for (int g = 0; g < 2; ++g) {
;       st.ol[g] *= scs[g];
; #pragma unroll
;       for (int dsub = 0; dsub < 4; ++dsub) st.o[g][dsub] *= scs[g];
;     }
;   }
;   pv_accum_t<true>(st.o, st.ol, s, Vt, fr, fq);
.LBB0_515:
	s_barrier
	v_sub_f32_e32 v126, v126, v248
	v_sub_f32_e32 v127, v127, v248
	v_sub_f32_e32 v116, v116, v247
	v_sub_f32_e32 v117, v117, v247
	v_sub_f32_e32 v110, v110, v247
	v_sub_f32_e32 v111, v111, v247
	v_sub_f32_e32 v112, v112, v247
	v_sub_f32_e32 v113, v113, v247
	v_exp_f32_e32 v126, v126
	v_exp_f32_e32 v127, v127
	v_exp_f32_e32 v116, v116
	v_exp_f32_e32 v117, v117
	v_exp_f32_e32 v110, v110
	v_exp_f32_e32 v111, v111
	v_exp_f32_e32 v112, v112
	v_exp_f32_e32 v113, v113
	v_sub_f32_e32 v118, v118, v248
	v_sub_f32_e32 v119, v119, v248
	v_sub_f32_e32 v120, v120, v248
	v_sub_f32_e32 v121, v121, v248
	v_sub_f32_e32 v114, v114, v247
	v_sub_f32_e32 v115, v115, v247
	v_exp_f32_e32 v118, v118
	v_exp_f32_e32 v119, v119
	v_exp_f32_e32 v120, v120
	v_exp_f32_e32 v121, v121
	v_exp_f32_e32 v114, v114
	v_exp_f32_e32 v115, v115
	v_cvt_pk_bf16_f32 v110, v110, v111
	v_cvt_pk_bf16_f32 v111, v112, v113
	v_cvt_pk_bf16_f32 v113, v116, v117
	v_cvt_pk_bf16_f32 v116, v126, v127
	v_lshl_add_u32 v126, s23, 1, v156
	v_add_u32_e32 v127, 0x4800, v126
	v_cvt_pk_bf16_f32 v112, v114, v115
	v_cvt_pk_bf16_f32 v114, v118, v119
	v_cvt_pk_bf16_f32 v115, v120, v121
	ds_read2_b64 v[118:121], v127 offset1:4
	v_sub_f32_e32 v128, v128, v248
	v_sub_f32_e32 v129, v129, v248
	v_exp_f32_e32 v128, v128
	v_exp_f32_e32 v129, v129
	s_waitcnt lgkmcnt(0)
	s_setprio 1
	v_mfma_f32_16x16x32_bf16 v[66:69], v[118:121], v[110:113], v[66:69]
	v_cvt_pk_bf16_f32 v117, v128, v129
	v_add_u32_e32 v128, 0x5000, v126
	v_add_u32_e32 v129, 0x5800, v126
	v_mfma_f32_16x16x32_bf16 v[78:81], v[118:121], v[114:117], v[78:81]
	ds_read2_b64 v[118:121], v128 offset0:32 offset1:36
	v_add_u32_e32 v126, 0x6000, v126
	v_sub_f32_e32 v138, v138, v248
	s_waitcnt lgkmcnt(0)
	v_mfma_f32_16x16x32_bf16 v[62:65], v[118:121], v[110:113], v[62:65]
	v_sub_f32_e32 v139, v139, v248
	v_sub_f32_e32 v140, v140, v248
	v_sub_f32_e32 v141, v141, v248
	v_mfma_f32_16x16x32_bf16 v[74:77], v[118:121], v[114:117], v[74:77]
	ds_read2_b64 v[118:121], v129 offset0:64 offset1:68
	v_sub_f32_e32 v130, v130, v248
	v_sub_f32_e32 v131, v131, v248
	s_waitcnt lgkmcnt(0)
	v_mfma_f32_16x16x32_bf16 v[58:61], v[118:121], v[110:113], v[58:61]
	v_sub_f32_e32 v132, v132, v248
	v_sub_f32_e32 v133, v133, v248
	v_sub_f32_e32 v134, v134, v247
	v_mfma_f32_16x16x32_bf16 v[70:73], v[118:121], v[114:117], v[70:73]
	ds_read2_b64 v[118:121], v126 offset0:96 offset1:100
	v_sub_f32_e32 v135, v135, v247
	v_sub_f32_e32 v136, v136, v247
	s_waitcnt lgkmcnt(0)
	v_mfma_f32_16x16x32_bf16 v[50:53], v[118:121], v[110:113], v[50:53]
	v_sub_f32_e32 v137, v137, v247
	v_sub_f32_e32 v122, v122, v247
	v_sub_f32_e32 v123, v123, v247
	v_mfma_f32_16x16x32_bf16 v[54:57], v[118:121], v[114:117], v[54:57]
	ds_read2_b64 v[118:121], v127 offset0:8 offset1:12
	v_sub_f32_e32 v124, v124, v247
	v_sub_f32_e32 v125, v125, v247
	v_exp_f32_e32 v138, v138
	v_exp_f32_e32 v139, v139
	v_exp_f32_e32 v140, v140
	v_exp_f32_e32 v141, v141
	v_exp_f32_e32 v130, v130
	v_exp_f32_e32 v131, v131
	v_exp_f32_e32 v132, v132
	v_exp_f32_e32 v133, v133
	v_exp_f32_e32 v134, v134
	v_exp_f32_e32 v135, v135
	v_exp_f32_e32 v136, v136
	v_exp_f32_e32 v137, v137
	v_exp_f32_e32 v122, v122
	v_exp_f32_e32 v123, v123
	v_exp_f32_e32 v124, v124
	v_exp_f32_e32 v125, v125
	v_mfma_f32_16x16x32_bf16 v[102:105], v[82:85], v[110:113], v[102:105]
	v_cvt_pk_bf16_f32 v110, v122, v123
	v_cvt_pk_bf16_f32 v112, v134, v135
	v_cvt_pk_bf16_f32 v111, v124, v125
	v_mfma_f32_16x16x32_bf16 v[106:109], v[82:85], v[114:117], v[106:109]
	v_cvt_pk_bf16_f32 v113, v136, v137
	v_cvt_pk_bf16_f32 v114, v130, v131
	v_cvt_pk_bf16_f32 v115, v132, v133
	v_cvt_pk_bf16_f32 v116, v138, v139
	v_cvt_pk_bf16_f32 v117, v140, v141
	s_waitcnt lgkmcnt(0)
	v_mfma_f32_16x16x32_bf16 v[66:69], v[118:121], v[110:113], v[66:69]
	v_mfma_f32_16x16x32_bf16 v[78:81], v[118:121], v[114:117], v[78:81]
	ds_read2_b64 v[118:121], v128 offset0:40 offset1:44
	s_waitcnt lgkmcnt(0)
	v_mfma_f32_16x16x32_bf16 v[62:65], v[118:121], v[110:113], v[62:65]
	v_mfma_f32_16x16x32_bf16 v[74:77], v[118:121], v[114:117], v[74:77]
	ds_read2_b64 v[118:121], v129 offset0:72 offset1:76
	s_waitcnt lgkmcnt(0)
	v_mfma_f32_16x16x32_bf16 v[58:61], v[118:121], v[110:113], v[58:61]
	v_mfma_f32_16x16x32_bf16 v[70:73], v[118:121], v[114:117], v[70:73]
	ds_read2_b64 v[118:121], v126 offset0:104 offset1:108
	v_mfma_f32_16x16x32_bf16 v[102:105], v[82:85], v[110:113], v[102:105]
	v_mfma_f32_16x16x32_bf16 v[106:109], v[82:85], v[114:117], v[106:109]
	s_waitcnt lgkmcnt(0)
	v_mfma_f32_16x16x32_bf16 v[50:53], v[118:121], v[110:113], v[50:53]
	v_mfma_f32_16x16x32_bf16 v[54:57], v[118:121], v[114:117], v[54:57]
	s_setprio 0
	s_branch .LBB0_503
; DEVI void nsa_item(const Params& p, int l, int item, char* lds_raw, volatile int* nsa_cnt) {
;     ...
;     for (int itx = 0; itx < niter; ++itx) {
;       const bool active = (rem != 0u);
;       if (active) { j = __ffs(rem) - 1; rem &= rem - 1; }
;       if (active) KV_STORE(kvo);
;       __syncthreads();
;       if (active) {
;         if (rem) {
;           int jn = __ffs(rem) - 1;
;           KV_LOAD(kbase, vbase, jn);
;         }
;         const bool insel = (mysel >> j) & 1u;
;         const int hi = insel ? ((j == qt) ? tokl : 63) : -1;
;         if (__builtin_amdgcn_ballot_w64(insel) != 0ull) attn_step(st, qf, Kb + kvo, Vb + kvo, hi, -1, fr, fq);
;         kvo ^= 64 * LS;
;       }
;     }
; #pragma unroll
;     for (int g = 0; g < 2; ++g) {
;       const float lsum = attn_rowsum(st, g);
;       float sc = (lsum > 0.f ? 1.f / lsum : 0.f) * gate[g][1];
; #pragma unroll
;       for (int d = 0; d < 4; ++d) fin[g][d] += st.o[g][d] * sc;
;     }
;   }
;   {
;     AttnState st;
;     attn_init(st);
;     const bfu* kbase = proj + tokbase * LDP + C_KW + h * 64;
;     const bfu* vbase = (const bfu*)(p.ws + OFF_VWT) + ((long)b * 128 + h * 64) * SEQ;
;     int j = qt - 8 < 0 ? 0 : qt - 8;
;     KV_LOAD(kbase, vbase, j);
;     for (; j <= qt; ++j) {
;       KV_STORE(kvo);
;       __syncthreads();
;       if (j < qt) {
;         int jn = j + 1;
;         KV_LOAD(kbase, vbase, jn);
.Lsel_inactive:
	s_barrier
	s_branch .LBB0_504
.LBB0_516:
	s_or_b64 exec, exec, s[66:67]
	v_readfirstlane_b32 s30, v220
	s_lshr_b32 s30, s30, 8
	s_cmp_lg_u32 s30, 0
	s_cbranch_scc1 .Lsel_skew_out
	s_barrier
.Lsel_skew_out:
.LBB0_517:
	s_or_b64 exec, exec, s[64:65]
	ds_bpermute_b32 v82, v201, v102
	ds_bpermute_b32 v83, v201, v106
	v_mov_b32_e32 v103, v106
	s_sub_i32 s23, 23, s28
	s_max_i32 s28, s23, 0
	v_mov_b32_e32 v113, 0
	s_waitcnt lgkmcnt(0)
	v_pk_add_f32 v[190:191], v[102:103], v[82:83]
	ds_bpermute_b32 v192, v202, v190
	ds_bpermute_b32 v193, v202, v191
	s_cmp_le_i32 s28, s25
	v_mov_b32_e32 v112, 0
	v_mov_b32_e32 v111, 0
	v_mov_b32_e32 v110, 0
	v_mov_b32_e32 v105, 0
	v_mov_b32_e32 v104, 0
	v_mov_b32_e32 v103, 0
	v_mov_b32_e32 v102, 0
	s_waitcnt vmcnt(1)
	v_mov_b32_e32 v97, 0
	v_mov_b32_e32 v96, 0
	v_mov_b32_e32 v95, 0
	v_mov_b32_e32 v94, 0
	s_waitcnt vmcnt(0)
	v_mov_b32_e32 v89, 0
	v_mov_b32_e32 v88, 0
	v_mov_b32_e32 v87, 0
	v_mov_b32_e32 v86, 0
	v_mov_b32_e32 v109, 0
	v_mov_b32_e32 v108, 0
	v_mov_b32_e32 v107, 0
	v_mov_b32_e32 v106, 0
	v_mov_b32_e32 v101, 0
	v_mov_b32_e32 v100, 0
	v_mov_b32_e32 v99, 0
	v_mov_b32_e32 v98, 0
	v_mov_b32_e32 v93, 0
	v_mov_b32_e32 v92, 0
	v_mov_b32_e32 v91, 0
	v_mov_b32_e32 v90, 0
	v_mov_b32_e32 v85, 0
	v_mov_b32_e32 v84, 0
	v_mov_b32_e32 v83, 0
	v_mov_b32_e32 v82, 0
	v_mov_b32_e32 v135, 0
	v_mov_b32_e32 v134, 0
	s_cbranch_scc0 .LBB0_480
	s_lshl_b32 s0, s20, 1
	v_readlane_b32 s1, v243, 20
	s_add_u32 s0, s1, s0
	v_readlane_b32 s1, v243, 21
	s_addc_u32 s1, s1, 0
	s_lshl_b32 s30, s28, 6
	v_lshl_add_u64 v[82:83], v[144:145], 1, s[0:1]
	v_lshl_add_u64 v[84:85], v[146:147], 1, s[0:1]
	s_lshl_b64 s[0:1], s[30:31], 1
	v_lshl_add_u64 v[86:87], v[84:85], 0, s[0:1]
	v_lshl_add_u64 v[88:89], v[82:83], 0, s[0:1]
	v_lshl_add_u64 v[86:87], v[86:87], 0, v[0:1]
	v_lshl_add_u64 v[88:89], v[88:89], 0, v[0:1]
	global_load_dwordx4 v[118:121], v[86:87], off
	global_load_dwordx4 v[122:125], v[88:89], off
	v_add_u32_e32 v88, s30, v142
	v_mov_b64_e32 v[86:87], s[36:37]
	v_mad_i64_i32 v[88:89], s[0:1], v88, s72, v[86:87]
	v_add_u32_e32 v90, s30, v186
	v_lshl_add_u64 v[88:89], v[88:89], 0, v[0:1]
	v_mad_i64_i32 v[86:87], s[0:1], v90, s72, v[86:87]
	v_lshl_add_u64 v[86:87], v[86:87], 0, v[0:1]
	global_load_dwordx4 v[126:129], v[88:89], off offset:2560
	global_load_dwordx4 v[130:133], v[86:87], off offset:2560
	s_movk_i32 s0, 0x48
	v_cmp_eq_u32_e32 vcc, 0, v153
	v_lshl_add_u64 v[194:195], v[82:83], 0, v[0:1]
	v_mul_lo_u32 v82, v186, s0
	v_cndmask_b32_e32 v83, 0, v228, vcc
	v_mov_b32_e32 v110, v1
	v_mov_b32_e32 v111, v1
	v_mov_b32_e32 v112, v1
	v_mov_b32_e32 v113, v1
	v_lshl_add_u64 v[196:197], v[84:85], 0, v[0:1]
	v_perm_b32 v114, v83, v83, s16
	v_lshlrev_b32_e32 v181, 1, v82
	v_mov_b64_e32 v[102:103], v[110:111]
	v_mov_b64_e32 v[94:95], v[110:111]
	v_mov_b64_e32 v[86:87], v[110:111]
	v_mov_b64_e32 v[106:107], v[110:111]
	v_mov_b64_e32 v[98:99], v[110:111]
	v_mov_b64_e32 v[90:91], v[110:111]
	v_mov_b64_e32 v[82:83], v[110:111]
	v_mov_b64_e32 v[140:141], v[112:113]
	v_mov_b64_e32 v[136:137], v[112:113]
	v_mov_b32_e32 v115, v114
	v_mov_b32_e32 v116, v114
	v_mov_b32_e32 v117, v114
	v_mov_b32_e32 v198, 0xf149f2ca
	v_mov_b64_e32 v[104:105], v[112:113]
	v_mov_b64_e32 v[96:97], v[112:113]
	v_mov_b64_e32 v[88:89], v[112:113]
	v_mov_b64_e32 v[108:109], v[112:113]
	v_mov_b64_e32 v[100:101], v[112:113]
	v_mov_b64_e32 v[92:93], v[112:113]
	v_mov_b64_e32 v[84:85], v[112:113]
	v_mov_b64_e32 v[138:139], v[110:111]
	v_mov_b64_e32 v[134:135], v[110:111]
	v_mov_b32_e32 v200, 0xf149f2ca
	v_readfirstlane_b32 s36, v220
	s_lshr_b32 s36, s36, 8
	s_cmp_lg_u32 s36, 1
	s_cbranch_scc1 .Lwin_skew_in
	s_barrier
.Lwin_skew_in:
.LBB0_519:
	s_cmp_ge_i32 s28, s25
	v_lshl_add_u32 v187, v179, 1, s26
	s_cselect_b64 s[36:37], -1, 0
	v_add3_u32 v142, v187, v181, v0
	s_and_b64 vcc, exec, s[36:37]
	s_waitcnt vmcnt(0)
	ds_write_b128 v142, v[130:133]
	ds_write_b128 v142, v[126:129] offset:4608
	ds_write_b128 v142, v[122:125] offset:18432
	ds_write_b128 v142, v[118:121] offset:23040
	s_waitcnt lgkmcnt(0)
	s_barrier
	s_cbranch_vccnz .LBB0_521
	s_add_i32 s0, s30, 64
	v_add_u32_e32 v120, s30, v186
	v_add_u32_e32 v118, 64, v120
	v_add_u32_e32 v120, 0x60, v120
	s_ashr_i32 s1, s0, 31
	v_mad_i64_i32 v[118:119], s[4:5], v118, s72, v[188:189]
	v_mad_i64_i32 v[120:121], s[4:5], v120, s72, v[188:189]
	s_lshl_b64 s[0:1], s[0:1], 1
	global_load_dwordx4 v[130:133], v[118:119], off offset:2560
	global_load_dwordx4 v[126:129], v[120:121], off offset:2560
	v_lshl_add_u64 v[118:119], v[194:195], 0, s[0:1]
	v_lshl_add_u64 v[120:121], v[196:197], 0, s[0:1]
	global_load_dwordx4 v[122:125], v[118:119], off
	s_nop 0
	global_load_dwordx4 v[118:121], v[120:121], off

; template <bool WITH_L>
; DEVI void pv_accum_t(f32x4 (&o)[2][4], f32x4 (&ol)[2], const f32x4 (&pr)[2][4], const bfu* Vt, int fr, int fq) {
; #pragma unroll
;   for (int kp = 0; kp < 2; ++kp) {
;     bf16x8 pf[2];
; #pragma unroll
;     for (int g = 0; g < 2; ++g) {
;       uint4 u;
;       u.x = pack2(pr[g][2 * kp][0], pr[g][2 * kp][1]);
;       u.y = pack2(pr[g][2 * kp][2], pr[g][2 * kp][3]);
;       u.z = pack2(pr[g][2 * kp + 1][0], pr[g][2 * kp + 1][1]);
;       u.w = pack2(pr[g][2 * kp + 1][2], pr[g][2 * kp + 1][3]);
;       pf[g] = *(bf16x8*)&u;
;     }
;     if constexpr (WITH_L) {
;       const short one = (fr == 0) ? (short)0x3F80 : (short)0;
;       const bf16x8 vones = {one, one, one, one, one, one, one, one};
; #pragma unroll
;       for (int g = 0; g < 2; ++g) ol[g] = __builtin_amdgcn_mfma_f32_16x16x32_bf16(vones, pf[g], ol[g], 0, 0, 0);
;     }
; #pragma unroll
;     for (int dsub = 0; dsub < 4; ++dsub) {
;       uint2 lo = *(const uint2*)(Vt + (dsub * 16 + fr) * LS + (2 * kp) * 16 + fq * 4);
;       uint2 hi = *(const uint2*)(Vt + (dsub * 16 + fr) * LS + (2 * kp + 1) * 16 + fq * 4);
;       uint4 u; u.x = lo.x; u.y = lo.y; u.z = hi.x; u.w = hi.y;
;       bf16x8 vf = *(bf16x8*)&u;
; #pragma unroll
;       for (int g = 0; g < 2; ++g) o[g][dsub] = __builtin_amdgcn_mfma_f32_16x16x32_bf16(vf, pf[g], o[g][dsub], 0, 0, 0);
;     }
;   }
; DEVI void attn_step(AttnState& st, const bf16x8 (&qf)[2][2], const bfu* Ks, const bfu* Vt, int hi, int lo, int fr, int fq) {
;     ...
;     float mn = fmaxf(st.m[g], mx);
;     float sc = __builtin_amdgcn_exp2f(st.m[g] - mn);
; #pragma unroll
;     for (int ksub = 0; ksub < 4; ++ksub)
; #pragma unroll
;       for (int j = 0; j < 4; ++j) s[g][ksub][j] = __builtin_amdgcn_exp2f(s[g][ksub][j] - mn);
;     st.m[g] = mn;
;     scs[g] = sc;
;   }
;   if (__builtin_amdgcn_ballot_w64((scs[0] != 1.f) || (scs[1] != 1.f)) != 0ull) {
; #pragma unroll
;     for (int g = 0; g < 2; ++g) {
;       st.ol[g] *= scs[g];
; #pragma unroll
;       for (int dsub = 0; dsub < 4; ++dsub) st.o[g][dsub] *= scs[g];
;     }
;   }
;   pv_accum_t<true>(st.o, st.ol, s, Vt, fr, fq);
.LBB0_525:
	s_barrier
	v_sub_f32_e32 v150, v150, v205
	v_sub_f32_e32 v151, v151, v205
	v_sub_f32_e32 v146, v146, v204
	v_sub_f32_e32 v147, v147, v204
	v_sub_f32_e32 v142, v142, v204
	v_sub_f32_e32 v143, v143, v204
	v_sub_f32_e32 v144, v144, v204
	v_sub_f32_e32 v145, v145, v204
	v_sub_f32_e32 v158, v158, v205
	v_sub_f32_e32 v159, v159, v205
	v_exp_f32_e32 v150, v150
	v_exp_f32_e32 v151, v151
	v_exp_f32_e32 v146, v146
	v_exp_f32_e32 v147, v147
	v_sub_f32_e32 v148, v148, v204
	v_sub_f32_e32 v149, v149, v204
	v_exp_f32_e32 v142, v142
	v_exp_f32_e32 v143, v143
	v_exp_f32_e32 v144, v144
	v_exp_f32_e32 v145, v145
	v_exp_f32_e32 v158, v158
	v_exp_f32_e32 v159, v159
	v_exp_f32_e32 v148, v148
	v_exp_f32_e32 v149, v149
	v_sub_f32_e32 v152, v152, v205
	v_sub_f32_e32 v153, v153, v205
	v_exp_f32_e32 v152, v152
	v_exp_f32_e32 v153, v153
	v_cvt_pk_bf16_f32 v142, v142, v143
	v_cvt_pk_bf16_f32 v143, v144, v145
	v_cvt_pk_bf16_f32 v144, v146, v147
	v_cvt_pk_bf16_f32 v146, v150, v151
	v_lshlrev_b32_e32 v150, 1, v203
	v_cvt_pk_bf16_f32 v145, v148, v149
	v_cvt_pk_bf16_f32 v148, v158, v159
	v_add3_u32 v158, v187, v199, v150
	v_add_u32_e32 v159, 0x4800, v158
	v_cvt_pk_bf16_f32 v147, v152, v153
	ds_read2_b64 v[150:153], v159 offset1:4
	v_sub_f32_e32 v160, v160, v205
	v_sub_f32_e32 v161, v161, v205
	v_exp_f32_e32 v160, v160
	v_exp_f32_e32 v161, v161
	s_waitcnt lgkmcnt(0)
	s_setprio 1
	v_mfma_f32_16x16x32_bf16 v[110:113], v[150:153], v[142:145], v[110:113]
	v_cvt_pk_bf16_f32 v149, v160, v161
	v_add_u32_e32 v160, 0x5000, v158
	v_add_u32_e32 v161, 0x5800, v158
	v_mfma_f32_16x16x32_bf16 v[106:109], v[150:153], v[146:149], v[106:109]
	ds_read2_b64 v[150:153], v160 offset0:32 offset1:36
	v_add_u32_e32 v158, 0x6000, v158
	v_sub_f32_e32 v170, v170, v205
	s_waitcnt lgkmcnt(0)
	v_mfma_f32_16x16x32_bf16 v[102:105], v[150:153], v[142:145], v[102:105]
	v_sub_f32_e32 v171, v171, v205
	v_sub_f32_e32 v172, v172, v205
	v_sub_f32_e32 v173, v173, v205
	v_mfma_f32_16x16x32_bf16 v[98:101], v[150:153], v[146:149], v[98:101]
	ds_read2_b64 v[150:153], v161 offset0:64 offset1:68
	v_sub_f32_e32 v162, v162, v205
	v_sub_f32_e32 v163, v163, v205
	s_waitcnt lgkmcnt(0)
	v_mfma_f32_16x16x32_bf16 v[94:97], v[150:153], v[142:145], v[94:97]
	v_sub_f32_e32 v164, v164, v205
	v_sub_f32_e32 v165, v165, v205
	v_sub_f32_e32 v166, v166, v204
	v_mfma_f32_16x16x32_bf16 v[90:93], v[150:153], v[146:149], v[90:93]
	ds_read2_b64 v[150:153], v158 offset0:96 offset1:100
	v_sub_f32_e32 v167, v167, v204
	v_sub_f32_e32 v168, v168, v204
	s_waitcnt lgkmcnt(0)
	v_mfma_f32_16x16x32_bf16 v[86:89], v[150:153], v[142:145], v[86:89]
	v_sub_f32_e32 v169, v169, v204
	v_sub_f32_e32 v154, v154, v204
	v_sub_f32_e32 v155, v155, v204
	v_mfma_f32_16x16x32_bf16 v[82:85], v[150:153], v[146:149], v[82:85]
	ds_read2_b64 v[150:153], v159 offset0:8 offset1:12
	v_sub_f32_e32 v156, v156, v204
	v_sub_f32_e32 v157, v157, v204
	v_exp_f32_e32 v170, v170
	v_exp_f32_e32 v171, v171
	v_exp_f32_e32 v172, v172
	v_exp_f32_e32 v173, v173
	v_exp_f32_e32 v162, v162
	v_exp_f32_e32 v163, v163
	v_exp_f32_e32 v164, v164
	v_exp_f32_e32 v165, v165
	v_exp_f32_e32 v166, v166
	v_exp_f32_e32 v167, v167
	v_exp_f32_e32 v168, v168
	v_exp_f32_e32 v169, v169
	v_exp_f32_e32 v154, v154
	v_exp_f32_e32 v155, v155
	v_exp_f32_e32 v156, v156
	v_exp_f32_e32 v157, v157
	v_mfma_f32_16x16x32_bf16 v[138:141], v[114:117], v[142:145], v[138:141]
	v_cvt_pk_bf16_f32 v142, v154, v155
	v_cvt_pk_bf16_f32 v144, v166, v167
	v_cvt_pk_bf16_f32 v143, v156, v157
	v_mfma_f32_16x16x32_bf16 v[134:137], v[114:117], v[146:149], v[134:137]
	v_cvt_pk_bf16_f32 v145, v168, v169
	v_cvt_pk_bf16_f32 v146, v162, v163
	v_cvt_pk_bf16_f32 v147, v164, v165
	v_cvt_pk_bf16_f32 v148, v170, v171
	v_cvt_pk_bf16_f32 v149, v172, v173
	s_waitcnt lgkmcnt(0)
	v_mfma_f32_16x16x32_bf16 v[110:113], v[150:153], v[142:145], v[110:113]
	v_xor_b32_e32 v179, 0x1200, v179
	s_add_i32 s28, s28, 1
	s_add_i32 s30, s30, 64
	v_mfma_f32_16x16x32_bf16 v[106:109], v[150:153], v[146:149], v[106:109]
	ds_read2_b64 v[150:153], v160 offset0:40 offset1:44
	s_andn2_b64 vcc, exec, s[36:37]
	s_waitcnt lgkmcnt(0)
	v_mfma_f32_16x16x32_bf16 v[102:105], v[150:153], v[142:145], v[102:105]
	v_mfma_f32_16x16x32_bf16 v[98:101], v[150:153], v[146:149], v[98:101]
	ds_read2_b64 v[150:153], v161 offset0:72 offset1:76
	s_waitcnt lgkmcnt(0)
	v_mfma_f32_16x16x32_bf16 v[94:97], v[150:153], v[142:145], v[94:97]
	v_mfma_f32_16x16x32_bf16 v[90:93], v[150:153], v[146:149], v[90:93]
	ds_read2_b64 v[150:153], v158 offset0:104 offset1:108
	v_mfma_f32_16x16x32_bf16 v[138:141], v[114:117], v[142:145], v[138:141]
	v_mfma_f32_16x16x32_bf16 v[134:137], v[114:117], v[146:149], v[134:137]
	s_waitcnt lgkmcnt(0)
	v_mfma_f32_16x16x32_bf16 v[86:89], v[150:153], v[142:145], v[86:89]
	v_mfma_f32_16x16x32_bf16 v[82:85], v[150:153], v[146:149], v[82:85]
	s_cbranch_vccz .LBB0_479
	v_mov_b32_e32 v198, v204
	v_mov_b32_e32 v200, v205
	s_setprio 0
	s_branch .LBB0_519
